# speedup vs baseline: 1.0015x; 1.0015x over previous
; __device__ __forceinline__ void phase_fox_attn(const Params& p, char* smem) {
;     ...
;         mx = fmaxf(mx, __shfl_xor(mx, 16));
;         mx = fmaxf(mx, __shfl_xor(mx, 32));
;         mx2[qb] = mx;
;       }
;       if (__any((mx2[0] > m[0] + 8.f) || (mx2[1] > m[1] + 8.f))) {
; #pragma unroll
;         for (int qb = 0; qb < 2; ++qb) {
;           const float mnew = fmaxf(m[qb], mx2[qb]);
;           const float alpha = (mnew == -INFINITY) ? 1.f : __builtin_amdgcn_exp2f(m[qb] - mnew);
;           m[qb] = mnew;
;           l[qb] *= alpha;
; #pragma unroll
;           for (int db = 0; db < 8; ++db) { o[db][qb][0] *= alpha; o[db][qb][1] *= alpha; o[db][qb][2] *= alpha; o[db][qb][3] *= alpha; }
;         }
;       }
.Lfox_join:
	v_max3_f32 v168, v170, v98, v99
	v_add_f32_e32 v169, 0x41000000, v138
	v_cmp_gt_f32_e32 vcc, v208, v169
	v_add_f32_e32 v169, 0x41000000, v137
	v_cmp_gt_f32_e64 s[4:5], v168, v169
	s_or_b64 vcc, vcc, s[4:5]
	s_cbranch_vccz .LBB0_200
	ds_bpermute_b32 v209, v194, v208
	ds_bpermute_b32 v169, v194, v168
	v_lshlrev_b32_e32 v170, 2, v195
	s_waitcnt lgkmcnt(0)
	v_max_f32_e32 v171, v208, v209
	v_max_f32_e32 v168, v168, v169
	ds_bpermute_b32 v172, v170, v171
	ds_bpermute_b32 v170, v170, v168
	s_waitcnt lgkmcnt(0)
	v_max_f32_e32 v169, v171, v172
	v_max_f32_e32 v168, v168, v170
	v_max_f32_e32 v169, v169, v169
	v_max_f32_e32 v170, v138, v138
	v_max_f32_e32 v170, v170, v169
	v_max_f32_e32 v168, v168, v168
	v_max_f32_e32 v169, v137, v137
	v_sub_f32_e32 v138, v138, v170
	v_max_f32_e32 v171, v169, v168
	v_exp_f32_e32 v138, v138
	v_sub_f32_e32 v137, v137, v171
	v_exp_f32_e32 v137, v137
	v_cmp_neq_f32_e32 vcc, s0, v170
	s_nop 1
	v_cndmask_b32_e32 v169, 1.0, v138, vcc
	v_cmp_neq_f32_e32 vcc, s0, v171
	v_mov_b32_e32 v138, v169
	v_pk_mul_f32 v[50:51], v[50:51], v[138:139] op_sel_hi:[1,0]
	v_cndmask_b32_e32 v168, 1.0, v137, vcc
	v_pk_mul_f32 v[48:49], v[48:49], v[138:139] op_sel_hi:[1,0]
	v_pk_mul_f32 v[54:55], v[54:55], v[138:139] op_sel_hi:[1,0]
	v_pk_mul_f32 v[52:53], v[52:53], v[138:139] op_sel_hi:[1,0]
	v_pk_mul_f32 v[58:59], v[58:59], v[138:139] op_sel_hi:[1,0]
	v_pk_mul_f32 v[56:57], v[56:57], v[138:139] op_sel_hi:[1,0]
	v_pk_mul_f32 v[62:63], v[62:63], v[138:139] op_sel_hi:[1,0]
	v_pk_mul_f32 v[60:61], v[60:61], v[138:139] op_sel_hi:[1,0]
	v_pk_mul_f32 v[46:47], v[46:47], v[138:139] op_sel_hi:[1,0]
	v_pk_mul_f32 v[44:45], v[44:45], v[138:139] op_sel_hi:[1,0]
	v_pk_mul_f32 v[42:43], v[42:43], v[138:139] op_sel_hi:[1,0]
	v_pk_mul_f32 v[40:41], v[40:41], v[138:139] op_sel_hi:[1,0]
	v_pk_mul_f32 v[38:39], v[38:39], v[138:139] op_sel_hi:[1,0]
	v_pk_mul_f32 v[36:37], v[36:37], v[138:139] op_sel_hi:[1,0]
	v_pk_mul_f32 v[34:35], v[34:35], v[138:139] op_sel_hi:[1,0]
	v_pk_mul_f32 v[32:33], v[32:33], v[138:139] op_sel_hi:[1,0]
	v_pk_mul_f32 v[108:109], v[108:109], v[168:169]
	v_pk_mul_f32 v[30:31], v[30:31], v[168:169] op_sel_hi:[1,0]
	v_pk_mul_f32 v[28:29], v[28:29], v[168:169] op_sel_hi:[1,0]
	v_pk_mul_f32 v[26:27], v[26:27], v[168:169] op_sel_hi:[1,0]
	v_pk_mul_f32 v[24:25], v[24:25], v[168:169] op_sel_hi:[1,0]
	v_pk_mul_f32 v[22:23], v[22:23], v[168:169] op_sel_hi:[1,0]
	v_pk_mul_f32 v[20:21], v[20:21], v[168:169] op_sel_hi:[1,0]
	v_pk_mul_f32 v[18:19], v[18:19], v[168:169] op_sel_hi:[1,0]
	v_pk_mul_f32 v[16:17], v[16:17], v[168:169] op_sel_hi:[1,0]
	v_pk_mul_f32 v[14:15], v[14:15], v[168:169] op_sel_hi:[1,0]
	v_pk_mul_f32 v[12:13], v[12:13], v[168:169] op_sel_hi:[1,0]
	v_pk_mul_f32 v[10:11], v[10:11], v[168:169] op_sel_hi:[1,0]
	v_pk_mul_f32 v[8:9], v[8:9], v[168:169] op_sel_hi:[1,0]
	v_pk_mul_f32 v[6:7], v[6:7], v[168:169] op_sel_hi:[1,0]
	v_pk_mul_f32 v[4:5], v[4:5], v[168:169] op_sel_hi:[1,0]
	v_pk_mul_f32 v[2:3], v[2:3], v[168:169] op_sel_hi:[1,0]
	v_pk_mul_f32 v[0:1], v[0:1], v[168:169] op_sel_hi:[1,0]
	v_mov_b32_e32 v137, v171
	v_mov_b32_e32 v138, v170
	s_branch .LBB0_200
